# SWA item epilogue: all 8 z loads issued up front (v182-195), counted vmcnt(7) instead of 8 serialized vmcnt(0) round trips
# speedup vs baseline: 1.0073x; 1.0073x over previous
; __device__ __forceinline__ unsigned pk_bf16(float lo, float hi) { const f32x2 v = {lo, hi}; const bf16v2 b = __builtin_convertvector(v, bf16v2); return __builtin_bit_cast(unsigned, b); }
; __device__ __forceinline__ float bf_lo(unsigned u) { return __uint_as_float(u << 16); }
; __device__ __forceinline__ float bf_hi(unsigned u) { return __uint_as_float(u & 0xffff0000u); }
; __device__ __forceinline__ float silu_f(float v) { return v * __builtin_amdgcn_rcpf(1.0f + __builtin_amdgcn_exp2f(-LOG2E * v)); }
; __device__ __forceinline__ float xsum32(float v) { const auto r = __builtin_amdgcn_permlane32_swap(__float_as_uint(v), __float_as_uint(v), false, false); return __uint_as_float(r[0]) + __uint_as_float(r[1]); }
; template <int HD, int DV, int HW, int MODE> ...
;     ...
;     const float lt = xsum32(l), inv = 1.0f / lt;
;     const size_t tok = tok0 + (size_t)r * (iw + ql);
;     if (MODE == 0) {
;         if (hh == 0) lsep[tok * 8] = m + __builtin_amdgcn_logf(lt);
; #pragma unroll
;         for (int t = 0; t < NTV; ++t)
; #pragma unroll
;             for (int i4 = 0; i4 < 4; ++i4) { u32x2 wv; wv.x = pk_bf16(O[t][4 * i4] * inv, O[t][4 * i4 + 1] * inv); wv.y = pk_bf16(O[t][4 * i4 + 2] * inv, O[t][4 * i4 + 3] * inv);
;                 *(u32x2*)(op + tok * old + 32 * t + 8 * i4 + 4 * hh) = wv; }
;     } else {
; #pragma unroll
;         for (int t = 0; t < NTV; ++t)
; #pragma unroll
;             for (int i4 = 0; i4 < 4; ++i4) { const int dv = 32 * t + 8 * i4 + 4 * hh; const u32x2 z = *(const u32x2*)(zp + tok * ld + dv);
;                 u32x2 wv; wv.x = pk_bf16(O[t][4 * i4] * inv * silu_f(bf_lo(z.x)), O[t][4 * i4 + 1] * inv * silu_f(bf_hi(z.x))); wv.y = pk_bf16(O[t][4 * i4 + 2] * inv * silu_f(bf_lo(z.y)), O[t][4 * i4 + 3] * inv * silu_f(bf_hi(z.y)));
;                 *(u32x2*)(op + tok * old + dv) = wv; }
.LBB0_157:
	v_mov_b32_e32 v1, v101
	s_nop 1
	v_permlane32_swap_b32_e32 v101, v1
	v_add_f32_e32 v1, v101, v1
	v_div_scale_f32 v2, s[22:23], v1, v1, 1.0
	v_rcp_f32_e32 v3, v2
	s_lshl_b32 s2, s46, 1
	s_add_u32 s4, s80, s2
	s_addc_u32 s5, s81, 0
	v_fma_f32 v4, -v2, v3, 1.0
	v_fmac_f32_e32 v3, v4, v3
	v_div_scale_f32 v4, vcc, 1.0, v1, 1.0
	v_mul_f32_e32 v5, v4, v3
	v_readlane_b32 s10, v253, 10
	v_fma_f32 v6, -v2, v5, v4
	s_add_u32 s10, s10, s2
	v_readlane_b32 s2, v253, 11
	v_fmac_f32_e32 v5, v6, v3
	s_addc_u32 s11, s2, 0
	v_fma_f32 v2, -v2, v5, v4
	v_div_fmas_f32 v2, v2, v3, v5
	v_lshl_add_u64 v[4:5], v[98:99], 1, s[10:11]
	v_lshlrev_b64 v[6:7], 11, v[96:97]
	v_mov_b32_e32 v101, v0
	v_lshl_add_u64 v[8:9], s[4:5], 0, v[6:7]
	v_lshl_add_u64 v[6:7], v[4:5], 0, v[100:101]
	global_load_dwordx2 v[4:5], v[6:7], off
	global_load_dwordx2 v[182:183], v[6:7], off offset:16
	global_load_dwordx2 v[184:185], v[6:7], off offset:32
	global_load_dwordx2 v[186:187], v[6:7], off offset:48
	global_load_dwordx2 v[188:189], v[6:7], off offset:64
	global_load_dwordx2 v[190:191], v[6:7], off offset:80
	global_load_dwordx2 v[192:193], v[6:7], off offset:96
	global_load_dwordx2 v[194:195], v[6:7], off offset:112
	v_div_fixup_f32 v2, v2, v1, 1.0
	v_pk_mul_f32 v[14:15], v[32:33], v[2:3] op_sel_hi:[1,0]
	v_readlane_b32 s2, v254, 49
	s_add_i32 s21, s21, s50
	s_add_i32 s15, s15, s2
	s_cmpk_gt_i32 s21, 0x7ff
	s_waitcnt vmcnt(7)
	v_lshlrev_b32_e32 v10, 16, v4
	v_mul_f32_e32 v1, 0xbfb8aa3b, v10
	v_exp_f32_e32 v1, v1
	v_and_b32_e32 v11, 0xffff0000, v4
	v_lshlrev_b32_e32 v4, 16, v5
	v_and_b32_e32 v5, 0xffff0000, v5
	v_add_f32_e32 v1, 1.0, v1
	v_rcp_f32_e32 v12, v1
	v_mul_f32_e32 v1, 0xbfb8aa3b, v11
	v_exp_f32_e32 v1, v1
	s_nop 0
	v_add_f32_e32 v1, 1.0, v1
	v_rcp_f32_e32 v13, v1
	v_mul_f32_e32 v1, 0xbfb8aa3b, v4
	v_exp_f32_e32 v1, v1
	v_pk_mul_f32 v[10:11], v[12:13], v[10:11]
	s_nop 0
	v_pk_mul_f32 v[10:11], v[14:15], v[10:11]
	v_add_f32_e32 v1, 1.0, v1
	v_rcp_f32_e32 v12, v1
	v_mul_f32_e32 v1, 0xbfb8aa3b, v5
	v_exp_f32_e32 v1, v1
	v_pk_mul_f32 v[14:15], v[34:35], v[2:3] op_sel_hi:[1,0]
	v_cvt_pk_bf16_f32 v10, v10, v11
	v_add_f32_e32 v1, 1.0, v1
	v_rcp_f32_e32 v13, v1
	s_nop 0
	v_pk_mul_f32 v[4:5], v[12:13], v[4:5]
	s_nop 0
	v_pk_mul_f32 v[4:5], v[14:15], v[4:5]
	v_pk_mul_f32 v[14:15], v[36:37], v[2:3] op_sel_hi:[1,0]
	v_cvt_pk_bf16_f32 v11, v4, v5
	v_lshl_add_u64 v[4:5], v[8:9], 0, v[100:101]
	s_nop 0
	global_store_dwordx2 v[4:5], v[10:11], off
	s_waitcnt vmcnt(7)
	v_lshlrev_b32_e32 v10, 16, v182
	v_mul_f32_e32 v1, 0xbfb8aa3b, v10
	v_exp_f32_e32 v1, v1
	v_and_b32_e32 v11, 0xffff0000, v182
	v_add_f32_e32 v1, 1.0, v1
	v_rcp_f32_e32 v12, v1
	v_mul_f32_e32 v1, 0xbfb8aa3b, v11
	v_exp_f32_e32 v1, v1
	s_nop 0
	v_add_f32_e32 v1, 1.0, v1
	v_rcp_f32_e32 v13, v1
	s_nop 0
	v_pk_mul_f32 v[10:11], v[12:13], v[10:11]
	s_nop 0
	v_pk_mul_f32 v[10:11], v[14:15], v[10:11]
	v_pk_mul_f32 v[14:15], v[38:39], v[2:3] op_sel_hi:[1,0]
	v_cvt_pk_bf16_f32 v8, v10, v11
	v_lshlrev_b32_e32 v10, 16, v183
	v_mul_f32_e32 v1, 0xbfb8aa3b, v10
	v_exp_f32_e32 v1, v1
	v_and_b32_e32 v11, 0xffff0000, v183
	v_add_f32_e32 v1, 1.0, v1
	v_rcp_f32_e32 v12, v1
	v_mul_f32_e32 v1, 0xbfb8aa3b, v11
	v_exp_f32_e32 v1, v1
	s_nop 0
	v_add_f32_e32 v1, 1.0, v1
	v_rcp_f32_e32 v13, v1
	s_nop 0
	v_pk_mul_f32 v[10:11], v[12:13], v[10:11]
	s_nop 0
	v_pk_mul_f32 v[10:11], v[14:15], v[10:11]
	v_pk_mul_f32 v[14:15], v[40:41], v[2:3] op_sel_hi:[1,0]
	v_cvt_pk_bf16_f32 v9, v10, v11
	global_store_dwordx2 v[4:5], v[8:9], off offset:16
	s_waitcnt vmcnt(7)
	v_lshlrev_b32_e32 v10, 16, v184
	v_mul_f32_e32 v1, 0xbfb8aa3b, v10
	v_exp_f32_e32 v1, v1
	v_and_b32_e32 v11, 0xffff0000, v184
	v_add_f32_e32 v1, 1.0, v1
	v_rcp_f32_e32 v12, v1
	v_mul_f32_e32 v1, 0xbfb8aa3b, v11
	v_exp_f32_e32 v1, v1
	s_nop 0
	v_add_f32_e32 v1, 1.0, v1
	v_rcp_f32_e32 v13, v1
	s_nop 0
	v_pk_mul_f32 v[10:11], v[12:13], v[10:11]
	s_nop 0
	v_pk_mul_f32 v[10:11], v[14:15], v[10:11]
	v_pk_mul_f32 v[14:15], v[42:43], v[2:3] op_sel_hi:[1,0]
	v_cvt_pk_bf16_f32 v8, v10, v11
	v_lshlrev_b32_e32 v10, 16, v185
	v_mul_f32_e32 v1, 0xbfb8aa3b, v10
	v_exp_f32_e32 v1, v1
	v_and_b32_e32 v11, 0xffff0000, v185
	v_add_f32_e32 v1, 1.0, v1
	v_rcp_f32_e32 v12, v1
	v_mul_f32_e32 v1, 0xbfb8aa3b, v11
	v_exp_f32_e32 v1, v1
	s_nop 0
	v_add_f32_e32 v1, 1.0, v1
	v_rcp_f32_e32 v13, v1
	s_nop 0
	v_pk_mul_f32 v[10:11], v[12:13], v[10:11]
	s_nop 0
	v_pk_mul_f32 v[10:11], v[14:15], v[10:11]
	v_pk_mul_f32 v[14:15], v[44:45], v[2:3] op_sel_hi:[1,0]
	v_cvt_pk_bf16_f32 v9, v10, v11
	global_store_dwordx2 v[4:5], v[8:9], off offset:32
	s_waitcnt vmcnt(7)
; __device__ __forceinline__ unsigned pk_bf16(float lo, float hi) { const f32x2 v = {lo, hi}; const bf16v2 b = __builtin_convertvector(v, bf16v2); return __builtin_bit_cast(unsigned, b); }
; __device__ __forceinline__ float bf_lo(unsigned u) { return __uint_as_float(u << 16); }
; __device__ __forceinline__ float bf_hi(unsigned u) { return __uint_as_float(u & 0xffff0000u); }
; __device__ __forceinline__ float silu_f(float v) { return v * __builtin_amdgcn_rcpf(1.0f + __builtin_amdgcn_exp2f(-LOG2E * v)); }
; template <int HD, int DV, int HW, int MODE> ...
;     ...
;     } else {
; #pragma unroll
;         for (int t = 0; t < NTV; ++t)
; #pragma unroll
;             for (int i4 = 0; i4 < 4; ++i4) { const int dv = 32 * t + 8 * i4 + 4 * hh; const u32x2 z = *(const u32x2*)(zp + tok * ld + dv);
;                 u32x2 wv; wv.x = pk_bf16(O[t][4 * i4] * inv * silu_f(bf_lo(z.x)), O[t][4 * i4 + 1] * inv * silu_f(bf_hi(z.x))); wv.y = pk_bf16(O[t][4 * i4 + 2] * inv * silu_f(bf_lo(z.y)), O[t][4 * i4 + 3] * inv * silu_f(bf_hi(z.y)));
;                 *(u32x2*)(op + tok * old + dv) = wv; }
;     }
;     __syncthreads();
	v_lshlrev_b32_e32 v10, 16, v186
	v_mul_f32_e32 v1, 0xbfb8aa3b, v10
	v_exp_f32_e32 v1, v1
	v_and_b32_e32 v11, 0xffff0000, v186
	v_add_f32_e32 v1, 1.0, v1
	v_rcp_f32_e32 v12, v1
	v_mul_f32_e32 v1, 0xbfb8aa3b, v11
	v_exp_f32_e32 v1, v1
	s_nop 0
	v_add_f32_e32 v1, 1.0, v1
	v_rcp_f32_e32 v13, v1
	s_nop 0
	v_pk_mul_f32 v[10:11], v[12:13], v[10:11]
	s_nop 0
	v_pk_mul_f32 v[10:11], v[14:15], v[10:11]
	v_pk_mul_f32 v[14:15], v[46:47], v[2:3] op_sel_hi:[1,0]
	v_cvt_pk_bf16_f32 v8, v10, v11
	v_lshlrev_b32_e32 v10, 16, v187
	v_mul_f32_e32 v1, 0xbfb8aa3b, v10
	v_exp_f32_e32 v1, v1
	v_and_b32_e32 v11, 0xffff0000, v187
	v_add_f32_e32 v1, 1.0, v1
	v_rcp_f32_e32 v12, v1
	v_mul_f32_e32 v1, 0xbfb8aa3b, v11
	v_exp_f32_e32 v1, v1
	s_nop 0
	v_add_f32_e32 v1, 1.0, v1
	v_rcp_f32_e32 v13, v1
	s_nop 0
	v_pk_mul_f32 v[10:11], v[12:13], v[10:11]
	s_nop 0
	v_pk_mul_f32 v[10:11], v[14:15], v[10:11]
	v_pk_mul_f32 v[14:15], v[16:17], v[2:3] op_sel_hi:[1,0]
	v_cvt_pk_bf16_f32 v9, v10, v11
	global_store_dwordx2 v[4:5], v[8:9], off offset:48
	s_waitcnt vmcnt(7)
	v_lshlrev_b32_e32 v10, 16, v188
	v_mul_f32_e32 v1, 0xbfb8aa3b, v10
	v_exp_f32_e32 v1, v1
	v_and_b32_e32 v11, 0xffff0000, v188
	v_add_f32_e32 v1, 1.0, v1
	v_rcp_f32_e32 v12, v1
	v_mul_f32_e32 v1, 0xbfb8aa3b, v11
	v_exp_f32_e32 v1, v1
	s_nop 0
	v_add_f32_e32 v1, 1.0, v1
	v_rcp_f32_e32 v13, v1
	s_nop 0
	v_pk_mul_f32 v[10:11], v[12:13], v[10:11]
	s_nop 0
	v_pk_mul_f32 v[10:11], v[14:15], v[10:11]
	v_pk_mul_f32 v[14:15], v[18:19], v[2:3] op_sel_hi:[1,0]
	v_cvt_pk_bf16_f32 v8, v10, v11
	v_lshlrev_b32_e32 v10, 16, v189
	v_mul_f32_e32 v1, 0xbfb8aa3b, v10
	v_exp_f32_e32 v1, v1
	v_and_b32_e32 v11, 0xffff0000, v189
	v_add_f32_e32 v1, 1.0, v1
	v_rcp_f32_e32 v12, v1
	v_mul_f32_e32 v1, 0xbfb8aa3b, v11
	v_exp_f32_e32 v1, v1
	s_nop 0
	v_add_f32_e32 v1, 1.0, v1
	v_rcp_f32_e32 v13, v1
	s_nop 0
	v_pk_mul_f32 v[10:11], v[12:13], v[10:11]
	s_nop 0
	v_pk_mul_f32 v[10:11], v[14:15], v[10:11]
	v_pk_mul_f32 v[14:15], v[20:21], v[2:3] op_sel_hi:[1,0]
	v_cvt_pk_bf16_f32 v9, v10, v11
	global_store_dwordx2 v[4:5], v[8:9], off offset:64
	s_waitcnt vmcnt(7)
	v_lshlrev_b32_e32 v10, 16, v190
	v_mul_f32_e32 v1, 0xbfb8aa3b, v10
	v_exp_f32_e32 v1, v1
	v_and_b32_e32 v11, 0xffff0000, v190
	v_add_f32_e32 v1, 1.0, v1
	v_rcp_f32_e32 v12, v1
	v_mul_f32_e32 v1, 0xbfb8aa3b, v11
	v_exp_f32_e32 v1, v1
	s_nop 0
	v_add_f32_e32 v1, 1.0, v1
	v_rcp_f32_e32 v13, v1
	s_nop 0
	v_pk_mul_f32 v[10:11], v[12:13], v[10:11]
	s_nop 0
	v_pk_mul_f32 v[10:11], v[14:15], v[10:11]
	v_pk_mul_f32 v[14:15], v[22:23], v[2:3] op_sel_hi:[1,0]
	v_cvt_pk_bf16_f32 v8, v10, v11
	v_lshlrev_b32_e32 v10, 16, v191
	v_mul_f32_e32 v1, 0xbfb8aa3b, v10
	v_exp_f32_e32 v1, v1
	v_and_b32_e32 v11, 0xffff0000, v191
	v_add_f32_e32 v1, 1.0, v1
	v_rcp_f32_e32 v12, v1
	v_mul_f32_e32 v1, 0xbfb8aa3b, v11
	v_exp_f32_e32 v1, v1
	s_nop 0
	v_add_f32_e32 v1, 1.0, v1
	v_rcp_f32_e32 v13, v1
	s_nop 0
	v_pk_mul_f32 v[10:11], v[12:13], v[10:11]
	s_nop 0
	v_pk_mul_f32 v[10:11], v[14:15], v[10:11]
	v_pk_mul_f32 v[14:15], v[24:25], v[2:3] op_sel_hi:[1,0]
	v_cvt_pk_bf16_f32 v9, v10, v11
	global_store_dwordx2 v[4:5], v[8:9], off offset:80
	s_waitcnt vmcnt(7)
	v_lshlrev_b32_e32 v10, 16, v192
	v_mul_f32_e32 v1, 0xbfb8aa3b, v10
	v_exp_f32_e32 v1, v1
	v_and_b32_e32 v11, 0xffff0000, v192
	v_add_f32_e32 v1, 1.0, v1
	v_rcp_f32_e32 v12, v1
	v_mul_f32_e32 v1, 0xbfb8aa3b, v11
	v_exp_f32_e32 v1, v1
	s_nop 0
	v_add_f32_e32 v1, 1.0, v1
	v_rcp_f32_e32 v13, v1
	s_nop 0
	v_pk_mul_f32 v[10:11], v[12:13], v[10:11]
	s_nop 0
	v_pk_mul_f32 v[10:11], v[14:15], v[10:11]
	v_pk_mul_f32 v[14:15], v[26:27], v[2:3] op_sel_hi:[1,0]
	v_cvt_pk_bf16_f32 v8, v10, v11
	v_lshlrev_b32_e32 v10, 16, v193
	v_mul_f32_e32 v1, 0xbfb8aa3b, v10
	v_exp_f32_e32 v1, v1
	v_and_b32_e32 v11, 0xffff0000, v193
	v_add_f32_e32 v1, 1.0, v1
	v_rcp_f32_e32 v12, v1
	v_mul_f32_e32 v1, 0xbfb8aa3b, v11
	v_exp_f32_e32 v1, v1
	s_nop 0
	v_add_f32_e32 v1, 1.0, v1
	v_rcp_f32_e32 v13, v1
	s_nop 0
	v_pk_mul_f32 v[10:11], v[12:13], v[10:11]
	s_nop 0
	v_pk_mul_f32 v[10:11], v[14:15], v[10:11]
	v_pk_mul_f32 v[12:13], v[28:29], v[2:3] op_sel_hi:[1,0]
	v_cvt_pk_bf16_f32 v9, v10, v11
	global_store_dwordx2 v[4:5], v[8:9], off offset:96
	v_pk_mul_f32 v[2:3], v[30:31], v[2:3] op_sel_hi:[1,0]
	s_waitcnt vmcnt(7)
	v_lshlrev_b32_e32 v8, 16, v194
	v_mul_f32_e32 v1, 0xbfb8aa3b, v8
	v_exp_f32_e32 v1, v1
	v_and_b32_e32 v9, 0xffff0000, v194
	v_add_f32_e32 v1, 1.0, v1
	v_rcp_f32_e32 v10, v1
	v_mul_f32_e32 v1, 0xbfb8aa3b, v9
	v_exp_f32_e32 v1, v1
	s_nop 0
	v_add_f32_e32 v1, 1.0, v1
	v_rcp_f32_e32 v11, v1
	s_nop 0
	v_pk_mul_f32 v[8:9], v[10:11], v[8:9]
	s_nop 0
	v_pk_mul_f32 v[8:9], v[12:13], v[8:9]
	s_nop 0
	v_cvt_pk_bf16_f32 v6, v8, v9
	v_lshlrev_b32_e32 v8, 16, v195
	v_mul_f32_e32 v1, 0xbfb8aa3b, v8
	v_exp_f32_e32 v1, v1
	v_and_b32_e32 v9, 0xffff0000, v195
	v_add_f32_e32 v1, 1.0, v1
	v_rcp_f32_e32 v10, v1
	v_mul_f32_e32 v1, 0xbfb8aa3b, v9
	v_exp_f32_e32 v1, v1
	s_nop 0
	v_add_f32_e32 v1, 1.0, v1
	v_rcp_f32_e32 v11, v1
	s_nop 0
	v_pk_mul_f32 v[8:9], v[10:11], v[8:9]
	s_nop 0
	v_pk_mul_f32 v[2:3], v[2:3], v[8:9]
	s_nop 0
	v_cvt_pk_bf16_f32 v7, v2, v3
	global_store_dwordx2 v[4:5], v[6:7], off offset:112
	s_barrier
	s_cbranch_scc1 .LBB0_64
